# v28 + GEMM V-state f32 epilogue: 8 scalar dword stores per chunk replaced by in-quad 4x4 DPP transpose + 2 dwordx4 stores
# baseline (speedup 1.0000x reference)
.LBB0_712:
	v_readlane_b32 s36, v240, 6
	v_readlane_b32 s37, v240, 7
	s_and_b64 s[42:43], s[36:37], s[0:1]
	s_lshl_b32 s11, s40, 8
	s_lshl_b64 s[0:1], s[6:7], 1
	v_or_b32_e32 v187, s86, v168
	s_add_u32 s36, s54, s0
	v_add_u32_e32 v122, s11, v187
	s_addc_u32 s37, s55, s1
	v_readlane_b32 s0, v240, 2
	v_ashrrev_i32_e32 v0, s81, v122
	s_mul_i32 s6, s41, s0
	v_add_u32_e32 v0, s6, v0
	v_mul_lo_u32 v124, v0, s10
	v_mov_b32_e32 v123, s86
	v_ashrrev_i32_e32 v125, 31, v124
	v_bitop3_b32 v186, v168, s2, v123 bitop3:0xc8
	v_lshlrev_b64 v[124:125], s81, v[124:125]
	v_lshl_add_u32 v126, v161, 3, s87
	v_or_b32_e32 v124, v124, v186
	v_lshlrev_b64 v[124:125], 6, v[124:125]
	v_add_u32_e32 v0, s39, v126
	v_lshl_add_u64 v[128:129], s[36:37], 0, v[124:125]
	v_ashrrev_i32_e32 v124, 5, v0
	v_ashrrev_i32_e32 v125, 31, v124
	v_lshlrev_b64 v[124:125], s30, v[124:125]
	v_and_b32_e32 v0, 31, v0
	v_lshl_add_u64 v[162:163], v[128:129], 0, v[124:125]
	v_lshlrev_b32_e32 v0, 1, v0
	v_readlane_b32 s1, v240, 3
	v_ashrrev_i32_e32 v123, 31, v122
	v_cvt_pk_bf16_f32 v156, v114, v115
	v_cvt_pk_bf16_f32 v157, v116, v117
	v_cvt_pk_bf16_f32 v158, v118, v119
	v_cvt_pk_bf16_f32 v159, v120, v121
	v_lshl_add_u64 v[162:163], v[162:163], 0, v[0:1]
	v_cndmask_b32_e64 v127, 0, 1, s[42:43]
	v_add_u32_e32 v177, s38, v126
	global_store_dwordx4 v[162:163], v[156:159], off
	v_cmp_ne_u32_e64 s[0:1], 1, v127
	s_andn2_b64 vcc, exec, s[42:43]
	v_lshl_add_u64 v[156:157], v[122:123], 2, s[66:67]
	v_ashrrev_i32_e32 v180, 31, v177
	v_mul_lo_u32 v178, s71, v177
	v_or_b32_e32 v176, 1, v177
	v_or_b32_e32 v174, 2, v177
	v_or_b32_e32 v172, 3, v177
	v_or_b32_e32 v170, 4, v177
	v_or_b32_e32 v167, 5, v177
	v_or_b32_e32 v163, 6, v177
	v_or_b32_e32 v162, 7, v177
	s_cbranch_vccnz .LBB0_714
	v_mul_lo_u32 v123, s70, v180
	v_and_b32_e32 v167, 3, v168
	v_or_b32_e32 v167, v177, v167
	s_mov_b32 vcc_lo, 0x55555555
	s_mov_b32 vcc_hi, 0x55555555
	v_cndmask_b32_dpp v176, v115, v114, vcc quad_perm:[1,0,3,2] row_mask:0xf bank_mask:0xf
	v_cndmask_b32_dpp v172, v117, v116, vcc quad_perm:[1,0,3,2] row_mask:0xf bank_mask:0xf
	s_mov_b32 vcc_lo, 0xaaaaaaaa
	s_mov_b32 vcc_hi, 0xaaaaaaaa
	v_cndmask_b32_dpp v174, v114, v115, vcc quad_perm:[1,0,3,2] row_mask:0xf bank_mask:0xf
	v_cndmask_b32_dpp v170, v116, v117, vcc quad_perm:[1,0,3,2] row_mask:0xf bank_mask:0xf
	s_mov_b32 vcc_lo, 0x33333333
	s_mov_b32 vcc_hi, 0x33333333
	s_nop 0
	v_cndmask_b32_dpp v114, v172, v176, vcc quad_perm:[2,3,0,1] row_mask:0xf bank_mask:0xf
	v_cndmask_b32_dpp v115, v170, v174, vcc quad_perm:[2,3,0,1] row_mask:0xf bank_mask:0xf
	s_mov_b32 vcc_lo, 0xcccccccc
	s_mov_b32 vcc_hi, 0xcccccccc
	v_cndmask_b32_dpp v116, v176, v172, vcc quad_perm:[2,3,0,1] row_mask:0xf bank_mask:0xf
	v_cndmask_b32_dpp v117, v174, v170, vcc quad_perm:[2,3,0,1] row_mask:0xf bank_mask:0xf
	s_mov_b32 vcc_lo, 0x55555555
	s_mov_b32 vcc_hi, 0x55555555
	v_cndmask_b32_dpp v176, v119, v118, vcc quad_perm:[1,0,3,2] row_mask:0xf bank_mask:0xf
	v_cndmask_b32_dpp v172, v121, v120, vcc quad_perm:[1,0,3,2] row_mask:0xf bank_mask:0xf
	s_mov_b32 vcc_lo, 0xaaaaaaaa
	s_mov_b32 vcc_hi, 0xaaaaaaaa
	v_cndmask_b32_dpp v174, v118, v119, vcc quad_perm:[1,0,3,2] row_mask:0xf bank_mask:0xf
	v_cndmask_b32_dpp v170, v120, v121, vcc quad_perm:[1,0,3,2] row_mask:0xf bank_mask:0xf
	s_mov_b32 vcc_lo, 0x33333333
	s_mov_b32 vcc_hi, 0x33333333
	s_nop 0
	v_cndmask_b32_dpp v118, v172, v176, vcc quad_perm:[2,3,0,1] row_mask:0xf bank_mask:0xf
	v_cndmask_b32_dpp v119, v170, v174, vcc quad_perm:[2,3,0,1] row_mask:0xf bank_mask:0xf
	s_mov_b32 vcc_lo, 0xcccccccc
	s_mov_b32 vcc_hi, 0xcccccccc
	v_cndmask_b32_dpp v120, v176, v172, vcc quad_perm:[2,3,0,1] row_mask:0xf bank_mask:0xf
	v_cndmask_b32_dpp v121, v174, v170, vcc quad_perm:[2,3,0,1] row_mask:0xf bank_mask:0xf
	v_mul_lo_u32 v163, s71, v167
	v_mad_u64_u32 v[158:159], s[42:43], s70, v167, 0
	v_add3_u32 v159, v159, v123, v163
	v_lshl_add_u64 v[158:159], v[158:159], 2, v[156:157]
	v_and_b32_e32 v158, 0xfffffff0, v158
	global_store_dwordx4 v[158:159], v[114:117], off
	v_or_b32_e32 v167, 4, v167
	v_mul_lo_u32 v163, s71, v167
	v_mad_u64_u32 v[158:159], s[42:43], s70, v167, 0
	v_add3_u32 v159, v159, v123, v163
	v_lshl_add_u64 v[158:159], v[158:159], 2, v[156:157]
	v_and_b32_e32 v158, 0xfffffff0, v158
	global_store_dwordx4 v[158:159], v[118:121], off
.LBB0_714:
	v_add_u32_e32 v123, 0x80, v126
	v_add_u32_e32 v169, s39, v123
	v_ashrrev_i32_e32 v126, 5, v169
	v_ashrrev_i32_e32 v127, 31, v126
	v_lshlrev_b64 v[126:127], s30, v[126:127]
	v_lshl_add_u64 v[158:159], v[128:129], 0, v[126:127]
	v_and_b32_e32 v128, 31, v169
	v_lshlrev_b32_e32 v128, 1, v128
	v_mov_b32_e32 v129, v1
	v_cvt_pk_bf16_f32 v182, v106, v107
	v_cvt_pk_bf16_f32 v183, v108, v109
	v_cvt_pk_bf16_f32 v184, v110, v111
	v_cvt_pk_bf16_f32 v185, v112, v113
	v_lshl_add_u64 v[158:159], v[158:159], 0, v[128:129]
	global_store_dwordx4 v[158:159], v[182:185], off
	s_and_b64 vcc, exec, s[0:1]
	s_nop 0
	v_add_u32_e32 v183, s38, v123
	v_ashrrev_i32_e32 v185, 31, v183
	v_mul_lo_u32 v184, s71, v183
	v_or_b32_e32 v182, 1, v183
	v_or_b32_e32 v181, 2, v183
	v_or_b32_e32 v179, 3, v183
	v_or_b32_e32 v175, 4, v183
	v_or_b32_e32 v173, 5, v183
	v_or_b32_e32 v171, 6, v183
	v_or_b32_e32 v169, 7, v183
	s_cbranch_vccnz .LBB0_716
	v_mul_lo_u32 v123, s70, v185
	v_and_b32_e32 v173, 3, v168
	v_or_b32_e32 v173, v183, v173
	s_mov_b32 vcc_lo, 0x55555555
	s_mov_b32 vcc_hi, 0x55555555
	v_cndmask_b32_dpp v182, v107, v106, vcc quad_perm:[1,0,3,2] row_mask:0xf bank_mask:0xf
	v_cndmask_b32_dpp v179, v109, v108, vcc quad_perm:[1,0,3,2] row_mask:0xf bank_mask:0xf
	s_mov_b32 vcc_lo, 0xaaaaaaaa
	s_mov_b32 vcc_hi, 0xaaaaaaaa
	v_cndmask_b32_dpp v181, v106, v107, vcc quad_perm:[1,0,3,2] row_mask:0xf bank_mask:0xf
	v_cndmask_b32_dpp v175, v108, v109, vcc quad_perm:[1,0,3,2] row_mask:0xf bank_mask:0xf
	s_mov_b32 vcc_lo, 0x33333333
	s_mov_b32 vcc_hi, 0x33333333
	s_nop 0
	v_cndmask_b32_dpp v106, v179, v182, vcc quad_perm:[2,3,0,1] row_mask:0xf bank_mask:0xf
	v_cndmask_b32_dpp v107, v175, v181, vcc quad_perm:[2,3,0,1] row_mask:0xf bank_mask:0xf
	s_mov_b32 vcc_lo, 0xcccccccc
	s_mov_b32 vcc_hi, 0xcccccccc
	v_cndmask_b32_dpp v108, v182, v179, vcc quad_perm:[2,3,0,1] row_mask:0xf bank_mask:0xf
	v_cndmask_b32_dpp v109, v181, v175, vcc quad_perm:[2,3,0,1] row_mask:0xf bank_mask:0xf
	s_mov_b32 vcc_lo, 0x55555555
	s_mov_b32 vcc_hi, 0x55555555
	v_cndmask_b32_dpp v182, v111, v110, vcc quad_perm:[1,0,3,2] row_mask:0xf bank_mask:0xf
	v_cndmask_b32_dpp v179, v113, v112, vcc quad_perm:[1,0,3,2] row_mask:0xf bank_mask:0xf
	s_mov_b32 vcc_lo, 0xaaaaaaaa
	s_mov_b32 vcc_hi, 0xaaaaaaaa
	v_cndmask_b32_dpp v181, v110, v111, vcc quad_perm:[1,0,3,2] row_mask:0xf bank_mask:0xf
	v_cndmask_b32_dpp v175, v112, v113, vcc quad_perm:[1,0,3,2] row_mask:0xf bank_mask:0xf
	s_mov_b32 vcc_lo, 0x33333333
	s_mov_b32 vcc_hi, 0x33333333
	s_nop 0
	v_cndmask_b32_dpp v110, v179, v182, vcc quad_perm:[2,3,0,1] row_mask:0xf bank_mask:0xf
	v_cndmask_b32_dpp v111, v175, v181, vcc quad_perm:[2,3,0,1] row_mask:0xf bank_mask:0xf
	s_mov_b32 vcc_lo, 0xcccccccc
	s_mov_b32 vcc_hi, 0xcccccccc
	v_cndmask_b32_dpp v112, v182, v179, vcc quad_perm:[2,3,0,1] row_mask:0xf bank_mask:0xf
	v_cndmask_b32_dpp v113, v181, v175, vcc quad_perm:[2,3,0,1] row_mask:0xf bank_mask:0xf
	v_mul_lo_u32 v171, s71, v173
	v_mad_u64_u32 v[158:159], s[38:39], s70, v173, 0
	v_add3_u32 v159, v159, v123, v171
	v_lshl_add_u64 v[158:159], v[158:159], 2, v[156:157]
	v_and_b32_e32 v158, 0xfffffff0, v158
	global_store_dwordx4 v[158:159], v[106:109], off
	v_or_b32_e32 v173, 4, v173
	v_mul_lo_u32 v171, s71, v173
	v_mad_u64_u32 v[158:159], s[38:39], s70, v173, 0
	v_add3_u32 v159, v159, v123, v171
	v_lshl_add_u64 v[158:159], v[158:159], 2, v[156:157]
	v_and_b32_e32 v158, 0xfffffff0, v158
	global_store_dwordx4 v[158:159], v[110:113], off
.LBB0_716:
	v_or_b32_e32 v123, 16, v187
	v_add_u32_e32 v156, s11, v123
	v_ashrrev_i32_e32 v129, s81, v156
	v_add_u32_e32 v129, s6, v129
	v_mul_lo_u32 v158, v129, s10
	v_ashrrev_i32_e32 v159, 31, v158
	v_lshlrev_b64 v[158:159], s81, v[158:159]
	v_and_or_b32 v158, v123, s2, v158
	v_lshlrev_b64 v[158:159], 6, v[158:159]
	v_lshl_add_u64 v[158:159], s[36:37], 0, v[158:159]
	v_ashrrev_i32_e32 v157, 31, v156
	v_lshl_add_u64 v[192:193], v[158:159], 0, v[124:125]
	v_cvt_pk_bf16_f32 v188, v98, v99
	v_cvt_pk_bf16_f32 v189, v100, v101
	v_cvt_pk_bf16_f32 v190, v102, v103
	v_cvt_pk_bf16_f32 v191, v104, v105
	v_lshl_add_u64 v[192:193], v[192:193], 0, v[0:1]
	s_and_b64 vcc, exec, s[0:1]
	v_lshl_add_u64 v[156:157], v[156:157], 2, s[66:67]
	global_store_dwordx4 v[192:193], v[188:191], off
	s_cbranch_vccnz .LBB0_718
	v_mul_lo_u32 v123, s70, v180
	v_and_b32_e32 v167, 3, v168
	v_or_b32_e32 v167, v177, v167
	s_mov_b32 vcc_lo, 0x55555555
	s_mov_b32 vcc_hi, 0x55555555
	v_cndmask_b32_dpp v176, v99, v98, vcc quad_perm:[1,0,3,2] row_mask:0xf bank_mask:0xf
	v_cndmask_b32_dpp v172, v101, v100, vcc quad_perm:[1,0,3,2] row_mask:0xf bank_mask:0xf
	s_mov_b32 vcc_lo, 0xaaaaaaaa
	s_mov_b32 vcc_hi, 0xaaaaaaaa
	v_cndmask_b32_dpp v174, v98, v99, vcc quad_perm:[1,0,3,2] row_mask:0xf bank_mask:0xf
	v_cndmask_b32_dpp v170, v100, v101, vcc quad_perm:[1,0,3,2] row_mask:0xf bank_mask:0xf
	s_mov_b32 vcc_lo, 0x33333333
	s_mov_b32 vcc_hi, 0x33333333
	s_nop 0
	v_cndmask_b32_dpp v98, v172, v176, vcc quad_perm:[2,3,0,1] row_mask:0xf bank_mask:0xf
	v_cndmask_b32_dpp v99, v170, v174, vcc quad_perm:[2,3,0,1] row_mask:0xf bank_mask:0xf
	s_mov_b32 vcc_lo, 0xcccccccc
	s_mov_b32 vcc_hi, 0xcccccccc
	v_cndmask_b32_dpp v100, v176, v172, vcc quad_perm:[2,3,0,1] row_mask:0xf bank_mask:0xf
	v_cndmask_b32_dpp v101, v174, v170, vcc quad_perm:[2,3,0,1] row_mask:0xf bank_mask:0xf
	s_mov_b32 vcc_lo, 0x55555555
	s_mov_b32 vcc_hi, 0x55555555
	v_cndmask_b32_dpp v176, v103, v102, vcc quad_perm:[1,0,3,2] row_mask:0xf bank_mask:0xf
	v_cndmask_b32_dpp v172, v105, v104, vcc quad_perm:[1,0,3,2] row_mask:0xf bank_mask:0xf
	s_mov_b32 vcc_lo, 0xaaaaaaaa
	s_mov_b32 vcc_hi, 0xaaaaaaaa
	v_cndmask_b32_dpp v174, v102, v103, vcc quad_perm:[1,0,3,2] row_mask:0xf bank_mask:0xf
	v_cndmask_b32_dpp v170, v104, v105, vcc quad_perm:[1,0,3,2] row_mask:0xf bank_mask:0xf
	s_mov_b32 vcc_lo, 0x33333333
	s_mov_b32 vcc_hi, 0x33333333
	s_nop 0
	v_cndmask_b32_dpp v102, v172, v176, vcc quad_perm:[2,3,0,1] row_mask:0xf bank_mask:0xf
	v_cndmask_b32_dpp v103, v170, v174, vcc quad_perm:[2,3,0,1] row_mask:0xf bank_mask:0xf
	s_mov_b32 vcc_lo, 0xcccccccc
	s_mov_b32 vcc_hi, 0xcccccccc
	v_cndmask_b32_dpp v104, v176, v172, vcc quad_perm:[2,3,0,1] row_mask:0xf bank_mask:0xf
	v_cndmask_b32_dpp v105, v174, v170, vcc quad_perm:[2,3,0,1] row_mask:0xf bank_mask:0xf
	v_mul_lo_u32 v163, s71, v167
	v_mad_u64_u32 v[188:189], s[38:39], s70, v167, 0
	v_add3_u32 v189, v189, v123, v163
	v_lshl_add_u64 v[188:189], v[188:189], 2, v[156:157]
	v_and_b32_e32 v188, 0xfffffff0, v188
	global_store_dwordx4 v[188:189], v[98:101], off
	v_or_b32_e32 v167, 4, v167
	v_mul_lo_u32 v163, s71, v167
	v_mad_u64_u32 v[188:189], s[38:39], s70, v167, 0
	v_add3_u32 v189, v189, v123, v163
	v_lshl_add_u64 v[188:189], v[188:189], 2, v[156:157]
	v_and_b32_e32 v188, 0xfffffff0, v188
	global_store_dwordx4 v[188:189], v[102:105], off
.LBB0_718:
	v_lshl_add_u64 v[158:159], v[158:159], 0, v[126:127]
	v_mov_b32_e32 v129, v1
	v_cvt_pk_bf16_f32 v188, v90, v91
	v_cvt_pk_bf16_f32 v189, v92, v93
	v_cvt_pk_bf16_f32 v190, v94, v95
	v_cvt_pk_bf16_f32 v191, v96, v97
	v_lshl_add_u64 v[158:159], v[158:159], 0, v[128:129]
	s_and_b64 vcc, exec, s[0:1]
	global_store_dwordx4 v[158:159], v[188:191], off
	s_cbranch_vccnz .LBB0_720
	v_mul_lo_u32 v123, s70, v185
	v_and_b32_e32 v173, 3, v168
	v_or_b32_e32 v173, v183, v173
	s_mov_b32 vcc_lo, 0x55555555
	s_mov_b32 vcc_hi, 0x55555555
	v_cndmask_b32_dpp v182, v91, v90, vcc quad_perm:[1,0,3,2] row_mask:0xf bank_mask:0xf
	v_cndmask_b32_dpp v179, v93, v92, vcc quad_perm:[1,0,3,2] row_mask:0xf bank_mask:0xf
	s_mov_b32 vcc_lo, 0xaaaaaaaa
	s_mov_b32 vcc_hi, 0xaaaaaaaa
	v_cndmask_b32_dpp v181, v90, v91, vcc quad_perm:[1,0,3,2] row_mask:0xf bank_mask:0xf
	v_cndmask_b32_dpp v175, v92, v93, vcc quad_perm:[1,0,3,2] row_mask:0xf bank_mask:0xf
	s_mov_b32 vcc_lo, 0x33333333
	s_mov_b32 vcc_hi, 0x33333333
	s_nop 0
	v_cndmask_b32_dpp v90, v179, v182, vcc quad_perm:[2,3,0,1] row_mask:0xf bank_mask:0xf
	v_cndmask_b32_dpp v91, v175, v181, vcc quad_perm:[2,3,0,1] row_mask:0xf bank_mask:0xf
	s_mov_b32 vcc_lo, 0xcccccccc
	s_mov_b32 vcc_hi, 0xcccccccc
	v_cndmask_b32_dpp v92, v182, v179, vcc quad_perm:[2,3,0,1] row_mask:0xf bank_mask:0xf
	v_cndmask_b32_dpp v93, v181, v175, vcc quad_perm:[2,3,0,1] row_mask:0xf bank_mask:0xf
	s_mov_b32 vcc_lo, 0x55555555
	s_mov_b32 vcc_hi, 0x55555555
	v_cndmask_b32_dpp v182, v95, v94, vcc quad_perm:[1,0,3,2] row_mask:0xf bank_mask:0xf
	v_cndmask_b32_dpp v179, v97, v96, vcc quad_perm:[1,0,3,2] row_mask:0xf bank_mask:0xf
	s_mov_b32 vcc_lo, 0xaaaaaaaa
	s_mov_b32 vcc_hi, 0xaaaaaaaa
	v_cndmask_b32_dpp v181, v94, v95, vcc quad_perm:[1,0,3,2] row_mask:0xf bank_mask:0xf
	v_cndmask_b32_dpp v175, v96, v97, vcc quad_perm:[1,0,3,2] row_mask:0xf bank_mask:0xf
	s_mov_b32 vcc_lo, 0x33333333
	s_mov_b32 vcc_hi, 0x33333333
	s_nop 0
	v_cndmask_b32_dpp v94, v179, v182, vcc quad_perm:[2,3,0,1] row_mask:0xf bank_mask:0xf
	v_cndmask_b32_dpp v95, v175, v181, vcc quad_perm:[2,3,0,1] row_mask:0xf bank_mask:0xf
	s_mov_b32 vcc_lo, 0xcccccccc
	s_mov_b32 vcc_hi, 0xcccccccc
	v_cndmask_b32_dpp v96, v182, v179, vcc quad_perm:[2,3,0,1] row_mask:0xf bank_mask:0xf
	v_cndmask_b32_dpp v97, v181, v175, vcc quad_perm:[2,3,0,1] row_mask:0xf bank_mask:0xf
	v_mul_lo_u32 v171, s71, v173
	v_mad_u64_u32 v[158:159], s[38:39], s70, v173, 0
	v_add3_u32 v159, v159, v123, v171
	v_lshl_add_u64 v[158:159], v[158:159], 2, v[156:157]
	v_and_b32_e32 v158, 0xfffffff0, v158
	global_store_dwordx4 v[158:159], v[90:93], off
	v_or_b32_e32 v173, 4, v173
	v_mul_lo_u32 v171, s71, v173
	v_mad_u64_u32 v[158:159], s[38:39], s70, v173, 0
	v_add3_u32 v159, v159, v123, v171
	v_lshl_add_u64 v[158:159], v[158:159], 2, v[156:157]
	v_and_b32_e32 v158, 0xfffffff0, v158
	global_store_dwordx4 v[158:159], v[94:97], off
.LBB0_720:
	v_or_b32_e32 v123, 32, v187
	v_add_u32_e32 v156, s11, v123
	v_ashrrev_i32_e32 v129, s81, v156
	v_add_u32_e32 v129, s6, v129
	v_mul_lo_u32 v158, v129, s10
	v_ashrrev_i32_e32 v159, 31, v158
	v_lshlrev_b64 v[158:159], s81, v[158:159]
	v_and_or_b32 v158, v123, s2, v158
	v_lshlrev_b64 v[158:159], 6, v[158:159]
	v_lshl_add_u64 v[158:159], s[36:37], 0, v[158:159]
	v_ashrrev_i32_e32 v157, 31, v156
	v_lshl_add_u64 v[192:193], v[158:159], 0, v[124:125]
	v_cvt_pk_bf16_f32 v188, v82, v83
	v_cvt_pk_bf16_f32 v189, v84, v85
	v_cvt_pk_bf16_f32 v190, v86, v87
	v_cvt_pk_bf16_f32 v191, v88, v89
	v_lshl_add_u64 v[192:193], v[192:193], 0, v[0:1]
	s_and_b64 vcc, exec, s[0:1]
	v_lshl_add_u64 v[156:157], v[156:157], 2, s[66:67]
	global_store_dwordx4 v[192:193], v[188:191], off
	s_cbranch_vccnz .LBB0_722
	v_mul_lo_u32 v123, s70, v180
	v_and_b32_e32 v167, 3, v168
	v_or_b32_e32 v167, v177, v167
	s_mov_b32 vcc_lo, 0x55555555
	s_mov_b32 vcc_hi, 0x55555555
	v_cndmask_b32_dpp v176, v83, v82, vcc quad_perm:[1,0,3,2] row_mask:0xf bank_mask:0xf
	v_cndmask_b32_dpp v172, v85, v84, vcc quad_perm:[1,0,3,2] row_mask:0xf bank_mask:0xf
	s_mov_b32 vcc_lo, 0xaaaaaaaa
	s_mov_b32 vcc_hi, 0xaaaaaaaa
	v_cndmask_b32_dpp v174, v82, v83, vcc quad_perm:[1,0,3,2] row_mask:0xf bank_mask:0xf
	v_cndmask_b32_dpp v170, v84, v85, vcc quad_perm:[1,0,3,2] row_mask:0xf bank_mask:0xf
	s_mov_b32 vcc_lo, 0x33333333
	s_mov_b32 vcc_hi, 0x33333333
	s_nop 0
	v_cndmask_b32_dpp v82, v172, v176, vcc quad_perm:[2,3,0,1] row_mask:0xf bank_mask:0xf
	v_cndmask_b32_dpp v83, v170, v174, vcc quad_perm:[2,3,0,1] row_mask:0xf bank_mask:0xf
	s_mov_b32 vcc_lo, 0xcccccccc
	s_mov_b32 vcc_hi, 0xcccccccc
	v_cndmask_b32_dpp v84, v176, v172, vcc quad_perm:[2,3,0,1] row_mask:0xf bank_mask:0xf
	v_cndmask_b32_dpp v85, v174, v170, vcc quad_perm:[2,3,0,1] row_mask:0xf bank_mask:0xf
	s_mov_b32 vcc_lo, 0x55555555
	s_mov_b32 vcc_hi, 0x55555555
	v_cndmask_b32_dpp v176, v87, v86, vcc quad_perm:[1,0,3,2] row_mask:0xf bank_mask:0xf
	v_cndmask_b32_dpp v172, v89, v88, vcc quad_perm:[1,0,3,2] row_mask:0xf bank_mask:0xf
	s_mov_b32 vcc_lo, 0xaaaaaaaa
	s_mov_b32 vcc_hi, 0xaaaaaaaa
	v_cndmask_b32_dpp v174, v86, v87, vcc quad_perm:[1,0,3,2] row_mask:0xf bank_mask:0xf
	v_cndmask_b32_dpp v170, v88, v89, vcc quad_perm:[1,0,3,2] row_mask:0xf bank_mask:0xf
	s_mov_b32 vcc_lo, 0x33333333
	s_mov_b32 vcc_hi, 0x33333333
	s_nop 0
	v_cndmask_b32_dpp v86, v172, v176, vcc quad_perm:[2,3,0,1] row_mask:0xf bank_mask:0xf
	v_cndmask_b32_dpp v87, v170, v174, vcc quad_perm:[2,3,0,1] row_mask:0xf bank_mask:0xf
	s_mov_b32 vcc_lo, 0xcccccccc
	s_mov_b32 vcc_hi, 0xcccccccc
	v_cndmask_b32_dpp v88, v176, v172, vcc quad_perm:[2,3,0,1] row_mask:0xf bank_mask:0xf
	v_cndmask_b32_dpp v89, v174, v170, vcc quad_perm:[2,3,0,1] row_mask:0xf bank_mask:0xf
	v_mul_lo_u32 v163, s71, v167
	v_mad_u64_u32 v[188:189], s[38:39], s70, v167, 0
	v_add3_u32 v189, v189, v123, v163
	v_lshl_add_u64 v[188:189], v[188:189], 2, v[156:157]
	v_and_b32_e32 v188, 0xfffffff0, v188
	global_store_dwordx4 v[188:189], v[82:85], off
	v_or_b32_e32 v167, 4, v167
	v_mul_lo_u32 v163, s71, v167
	v_mad_u64_u32 v[188:189], s[38:39], s70, v167, 0
	v_add3_u32 v189, v189, v123, v163
	v_lshl_add_u64 v[188:189], v[188:189], 2, v[156:157]
	v_and_b32_e32 v188, 0xfffffff0, v188
	global_store_dwordx4 v[188:189], v[86:89], off
.LBB0_722:
	v_lshl_add_u64 v[158:159], v[158:159], 0, v[126:127]
	v_mov_b32_e32 v129, v1
	v_cvt_pk_bf16_f32 v188, v74, v75
	v_cvt_pk_bf16_f32 v189, v76, v77
	v_cvt_pk_bf16_f32 v190, v78, v79
	v_cvt_pk_bf16_f32 v191, v80, v81
	v_lshl_add_u64 v[158:159], v[158:159], 0, v[128:129]
	s_and_b64 vcc, exec, s[0:1]
	global_store_dwordx4 v[158:159], v[188:191], off
	s_cbranch_vccnz .LBB0_724
	v_mul_lo_u32 v123, s70, v185
	v_and_b32_e32 v173, 3, v168
	v_or_b32_e32 v173, v183, v173
	s_mov_b32 vcc_lo, 0x55555555
	s_mov_b32 vcc_hi, 0x55555555
	v_cndmask_b32_dpp v182, v75, v74, vcc quad_perm:[1,0,3,2] row_mask:0xf bank_mask:0xf
	v_cndmask_b32_dpp v179, v77, v76, vcc quad_perm:[1,0,3,2] row_mask:0xf bank_mask:0xf
	s_mov_b32 vcc_lo, 0xaaaaaaaa
	s_mov_b32 vcc_hi, 0xaaaaaaaa
	v_cndmask_b32_dpp v181, v74, v75, vcc quad_perm:[1,0,3,2] row_mask:0xf bank_mask:0xf
	v_cndmask_b32_dpp v175, v76, v77, vcc quad_perm:[1,0,3,2] row_mask:0xf bank_mask:0xf
	s_mov_b32 vcc_lo, 0x33333333
	s_mov_b32 vcc_hi, 0x33333333
	s_nop 0
	v_cndmask_b32_dpp v74, v179, v182, vcc quad_perm:[2,3,0,1] row_mask:0xf bank_mask:0xf
	v_cndmask_b32_dpp v75, v175, v181, vcc quad_perm:[2,3,0,1] row_mask:0xf bank_mask:0xf
	s_mov_b32 vcc_lo, 0xcccccccc
	s_mov_b32 vcc_hi, 0xcccccccc
	v_cndmask_b32_dpp v76, v182, v179, vcc quad_perm:[2,3,0,1] row_mask:0xf bank_mask:0xf
	v_cndmask_b32_dpp v77, v181, v175, vcc quad_perm:[2,3,0,1] row_mask:0xf bank_mask:0xf
	s_mov_b32 vcc_lo, 0x55555555
	s_mov_b32 vcc_hi, 0x55555555
	v_cndmask_b32_dpp v182, v79, v78, vcc quad_perm:[1,0,3,2] row_mask:0xf bank_mask:0xf
	v_cndmask_b32_dpp v179, v81, v80, vcc quad_perm:[1,0,3,2] row_mask:0xf bank_mask:0xf
	s_mov_b32 vcc_lo, 0xaaaaaaaa
	s_mov_b32 vcc_hi, 0xaaaaaaaa
	v_cndmask_b32_dpp v181, v78, v79, vcc quad_perm:[1,0,3,2] row_mask:0xf bank_mask:0xf
	v_cndmask_b32_dpp v175, v80, v81, vcc quad_perm:[1,0,3,2] row_mask:0xf bank_mask:0xf
	s_mov_b32 vcc_lo, 0x33333333
	s_mov_b32 vcc_hi, 0x33333333
	s_nop 0
	v_cndmask_b32_dpp v78, v179, v182, vcc quad_perm:[2,3,0,1] row_mask:0xf bank_mask:0xf
	v_cndmask_b32_dpp v79, v175, v181, vcc quad_perm:[2,3,0,1] row_mask:0xf bank_mask:0xf
	s_mov_b32 vcc_lo, 0xcccccccc
	s_mov_b32 vcc_hi, 0xcccccccc
	v_cndmask_b32_dpp v80, v182, v179, vcc quad_perm:[2,3,0,1] row_mask:0xf bank_mask:0xf
	v_cndmask_b32_dpp v81, v181, v175, vcc quad_perm:[2,3,0,1] row_mask:0xf bank_mask:0xf
	v_mul_lo_u32 v171, s71, v173
	v_mad_u64_u32 v[158:159], s[38:39], s70, v173, 0
	v_add3_u32 v159, v159, v123, v171
	v_lshl_add_u64 v[158:159], v[158:159], 2, v[156:157]
	v_and_b32_e32 v158, 0xfffffff0, v158
	global_store_dwordx4 v[158:159], v[74:77], off
	v_or_b32_e32 v173, 4, v173
	v_mul_lo_u32 v171, s71, v173
	v_mad_u64_u32 v[158:159], s[38:39], s70, v173, 0
	v_add3_u32 v159, v159, v123, v171
	v_lshl_add_u64 v[158:159], v[158:159], 2, v[156:157]
	v_and_b32_e32 v158, 0xfffffff0, v158
	global_store_dwordx4 v[158:159], v[78:81], off
.LBB0_724:
	v_or_b32_e32 v123, 48, v187
	v_add_u32_e32 v156, s11, v123
	v_ashrrev_i32_e32 v129, s81, v156
	v_add_u32_e32 v129, s6, v129
	v_mul_lo_u32 v158, v129, s10
	v_ashrrev_i32_e32 v159, 31, v158
	v_lshlrev_b64 v[158:159], s81, v[158:159]
	v_and_or_b32 v158, v123, s2, v158
	v_lshlrev_b64 v[158:159], 6, v[158:159]
	v_lshl_add_u64 v[158:159], s[36:37], 0, v[158:159]
	v_ashrrev_i32_e32 v157, 31, v156
	v_lshl_add_u64 v[192:193], v[158:159], 0, v[124:125]
	v_cvt_pk_bf16_f32 v188, v66, v67
	v_cvt_pk_bf16_f32 v189, v68, v69
	v_cvt_pk_bf16_f32 v190, v70, v71
	v_cvt_pk_bf16_f32 v191, v72, v73
	v_lshl_add_u64 v[192:193], v[192:193], 0, v[0:1]
	s_and_b64 vcc, exec, s[0:1]
	v_lshl_add_u64 v[156:157], v[156:157], 2, s[66:67]
	global_store_dwordx4 v[192:193], v[188:191], off
	s_cbranch_vccnz .LBB0_726
	v_mul_lo_u32 v123, s70, v180
	v_and_b32_e32 v167, 3, v168
	v_or_b32_e32 v167, v177, v167
	s_mov_b32 vcc_lo, 0x55555555
	s_mov_b32 vcc_hi, 0x55555555
	v_cndmask_b32_dpp v176, v67, v66, vcc quad_perm:[1,0,3,2] row_mask:0xf bank_mask:0xf
	v_cndmask_b32_dpp v172, v69, v68, vcc quad_perm:[1,0,3,2] row_mask:0xf bank_mask:0xf
	s_mov_b32 vcc_lo, 0xaaaaaaaa
	s_mov_b32 vcc_hi, 0xaaaaaaaa
	v_cndmask_b32_dpp v174, v66, v67, vcc quad_perm:[1,0,3,2] row_mask:0xf bank_mask:0xf
	v_cndmask_b32_dpp v170, v68, v69, vcc quad_perm:[1,0,3,2] row_mask:0xf bank_mask:0xf
	s_mov_b32 vcc_lo, 0x33333333
	s_mov_b32 vcc_hi, 0x33333333
	s_nop 0
	v_cndmask_b32_dpp v66, v172, v176, vcc quad_perm:[2,3,0,1] row_mask:0xf bank_mask:0xf
	v_cndmask_b32_dpp v67, v170, v174, vcc quad_perm:[2,3,0,1] row_mask:0xf bank_mask:0xf
	s_mov_b32 vcc_lo, 0xcccccccc
	s_mov_b32 vcc_hi, 0xcccccccc
	v_cndmask_b32_dpp v68, v176, v172, vcc quad_perm:[2,3,0,1] row_mask:0xf bank_mask:0xf
	v_cndmask_b32_dpp v69, v174, v170, vcc quad_perm:[2,3,0,1] row_mask:0xf bank_mask:0xf
	s_mov_b32 vcc_lo, 0x55555555
	s_mov_b32 vcc_hi, 0x55555555
	v_cndmask_b32_dpp v176, v71, v70, vcc quad_perm:[1,0,3,2] row_mask:0xf bank_mask:0xf
	v_cndmask_b32_dpp v172, v73, v72, vcc quad_perm:[1,0,3,2] row_mask:0xf bank_mask:0xf
	s_mov_b32 vcc_lo, 0xaaaaaaaa
	s_mov_b32 vcc_hi, 0xaaaaaaaa
	v_cndmask_b32_dpp v174, v70, v71, vcc quad_perm:[1,0,3,2] row_mask:0xf bank_mask:0xf
	v_cndmask_b32_dpp v170, v72, v73, vcc quad_perm:[1,0,3,2] row_mask:0xf bank_mask:0xf
	s_mov_b32 vcc_lo, 0x33333333
	s_mov_b32 vcc_hi, 0x33333333
	s_nop 0
	v_cndmask_b32_dpp v70, v172, v176, vcc quad_perm:[2,3,0,1] row_mask:0xf bank_mask:0xf
	v_cndmask_b32_dpp v71, v170, v174, vcc quad_perm:[2,3,0,1] row_mask:0xf bank_mask:0xf
	s_mov_b32 vcc_lo, 0xcccccccc
	s_mov_b32 vcc_hi, 0xcccccccc
	v_cndmask_b32_dpp v72, v176, v172, vcc quad_perm:[2,3,0,1] row_mask:0xf bank_mask:0xf
	v_cndmask_b32_dpp v73, v174, v170, vcc quad_perm:[2,3,0,1] row_mask:0xf bank_mask:0xf
	v_mul_lo_u32 v163, s71, v167
	v_mad_u64_u32 v[188:189], s[38:39], s70, v167, 0
	v_add3_u32 v189, v189, v123, v163
	v_lshl_add_u64 v[188:189], v[188:189], 2, v[156:157]
	v_and_b32_e32 v188, 0xfffffff0, v188
	global_store_dwordx4 v[188:189], v[66:69], off
	v_or_b32_e32 v167, 4, v167
	v_mul_lo_u32 v163, s71, v167
	v_mad_u64_u32 v[188:189], s[38:39], s70, v167, 0
	v_add3_u32 v189, v189, v123, v163
	v_lshl_add_u64 v[188:189], v[188:189], 2, v[156:157]
	v_and_b32_e32 v188, 0xfffffff0, v188
	global_store_dwordx4 v[188:189], v[70:73], off
.LBB0_726:
	v_lshl_add_u64 v[158:159], v[158:159], 0, v[126:127]
	v_mov_b32_e32 v129, v1
	v_cvt_pk_bf16_f32 v188, v58, v59
	v_cvt_pk_bf16_f32 v189, v60, v61
	v_cvt_pk_bf16_f32 v190, v62, v63
	v_cvt_pk_bf16_f32 v191, v64, v65
	v_lshl_add_u64 v[158:159], v[158:159], 0, v[128:129]
	s_and_b64 vcc, exec, s[0:1]
	global_store_dwordx4 v[158:159], v[188:191], off
	s_cbranch_vccnz .LBB0_728
	v_mul_lo_u32 v123, s70, v185
	v_and_b32_e32 v173, 3, v168
	v_or_b32_e32 v173, v183, v173
	s_mov_b32 vcc_lo, 0x55555555
	s_mov_b32 vcc_hi, 0x55555555
	v_cndmask_b32_dpp v182, v59, v58, vcc quad_perm:[1,0,3,2] row_mask:0xf bank_mask:0xf
	v_cndmask_b32_dpp v179, v61, v60, vcc quad_perm:[1,0,3,2] row_mask:0xf bank_mask:0xf
	s_mov_b32 vcc_lo, 0xaaaaaaaa
	s_mov_b32 vcc_hi, 0xaaaaaaaa
	v_cndmask_b32_dpp v181, v58, v59, vcc quad_perm:[1,0,3,2] row_mask:0xf bank_mask:0xf
	v_cndmask_b32_dpp v175, v60, v61, vcc quad_perm:[1,0,3,2] row_mask:0xf bank_mask:0xf
	s_mov_b32 vcc_lo, 0x33333333
	s_mov_b32 vcc_hi, 0x33333333
	s_nop 0
	v_cndmask_b32_dpp v58, v179, v182, vcc quad_perm:[2,3,0,1] row_mask:0xf bank_mask:0xf
	v_cndmask_b32_dpp v59, v175, v181, vcc quad_perm:[2,3,0,1] row_mask:0xf bank_mask:0xf
	s_mov_b32 vcc_lo, 0xcccccccc
	s_mov_b32 vcc_hi, 0xcccccccc
	v_cndmask_b32_dpp v60, v182, v179, vcc quad_perm:[2,3,0,1] row_mask:0xf bank_mask:0xf
	v_cndmask_b32_dpp v61, v181, v175, vcc quad_perm:[2,3,0,1] row_mask:0xf bank_mask:0xf
	s_mov_b32 vcc_lo, 0x55555555
	s_mov_b32 vcc_hi, 0x55555555
	v_cndmask_b32_dpp v182, v63, v62, vcc quad_perm:[1,0,3,2] row_mask:0xf bank_mask:0xf
	v_cndmask_b32_dpp v179, v65, v64, vcc quad_perm:[1,0,3,2] row_mask:0xf bank_mask:0xf
	s_mov_b32 vcc_lo, 0xaaaaaaaa
	s_mov_b32 vcc_hi, 0xaaaaaaaa
	v_cndmask_b32_dpp v181, v62, v63, vcc quad_perm:[1,0,3,2] row_mask:0xf bank_mask:0xf
	v_cndmask_b32_dpp v175, v64, v65, vcc quad_perm:[1,0,3,2] row_mask:0xf bank_mask:0xf
	s_mov_b32 vcc_lo, 0x33333333
	s_mov_b32 vcc_hi, 0x33333333
	s_nop 0
	v_cndmask_b32_dpp v62, v179, v182, vcc quad_perm:[2,3,0,1] row_mask:0xf bank_mask:0xf
	v_cndmask_b32_dpp v63, v175, v181, vcc quad_perm:[2,3,0,1] row_mask:0xf bank_mask:0xf
	s_mov_b32 vcc_lo, 0xcccccccc
	s_mov_b32 vcc_hi, 0xcccccccc
	v_cndmask_b32_dpp v64, v182, v179, vcc quad_perm:[2,3,0,1] row_mask:0xf bank_mask:0xf
	v_cndmask_b32_dpp v65, v181, v175, vcc quad_perm:[2,3,0,1] row_mask:0xf bank_mask:0xf
	v_mul_lo_u32 v171, s71, v173
	v_mad_u64_u32 v[158:159], s[38:39], s70, v173, 0
	v_add3_u32 v159, v159, v123, v171
	v_lshl_add_u64 v[158:159], v[158:159], 2, v[156:157]
	v_and_b32_e32 v158, 0xfffffff0, v158
	global_store_dwordx4 v[158:159], v[58:61], off
	v_or_b32_e32 v173, 4, v173
	v_mul_lo_u32 v171, s71, v173
	v_mad_u64_u32 v[158:159], s[38:39], s70, v173, 0
	v_add3_u32 v159, v159, v123, v171
	v_lshl_add_u64 v[158:159], v[158:159], 2, v[156:157]
	v_and_b32_e32 v158, 0xfffffff0, v158
	global_store_dwordx4 v[158:159], v[62:65], off
.LBB0_728:
	v_add_u32_e32 v156, 0x80, v122
	v_ashrrev_i32_e32 v123, s81, v156
	v_add_u32_e32 v123, s6, v123
	v_mul_lo_u32 v158, v123, s10
	v_ashrrev_i32_e32 v159, 31, v158
	v_lshlrev_b64 v[158:159], s81, v[158:159]
	v_or_b32_e32 v158, v158, v186
	v_lshlrev_b64 v[158:159], 6, v[158:159]
	v_lshl_add_u64 v[158:159], s[36:37], 0, v[158:159]
	v_ashrrev_i32_e32 v157, 31, v156
	v_lshl_add_u64 v[190:191], v[158:159], 0, v[124:125]
	v_cvt_pk_bf16_f32 v186, v50, v51
	v_cvt_pk_bf16_f32 v187, v52, v53
	v_cvt_pk_bf16_f32 v188, v54, v55
	v_cvt_pk_bf16_f32 v189, v56, v57
	v_lshl_add_u64 v[190:191], v[190:191], 0, v[0:1]
	s_and_b64 vcc, exec, s[0:1]
	v_lshl_add_u64 v[156:157], v[156:157], 2, s[66:67]
	global_store_dwordx4 v[190:191], v[186:189], off
	s_cbranch_vccnz .LBB0_730
	v_mul_lo_u32 v123, s70, v180
	v_and_b32_e32 v167, 3, v168
	v_or_b32_e32 v167, v177, v167
	s_mov_b32 vcc_lo, 0x55555555
	s_mov_b32 vcc_hi, 0x55555555
	v_cndmask_b32_dpp v176, v51, v50, vcc quad_perm:[1,0,3,2] row_mask:0xf bank_mask:0xf
	v_cndmask_b32_dpp v172, v53, v52, vcc quad_perm:[1,0,3,2] row_mask:0xf bank_mask:0xf
	s_mov_b32 vcc_lo, 0xaaaaaaaa
	s_mov_b32 vcc_hi, 0xaaaaaaaa
	v_cndmask_b32_dpp v174, v50, v51, vcc quad_perm:[1,0,3,2] row_mask:0xf bank_mask:0xf
	v_cndmask_b32_dpp v170, v52, v53, vcc quad_perm:[1,0,3,2] row_mask:0xf bank_mask:0xf
	s_mov_b32 vcc_lo, 0x33333333
	s_mov_b32 vcc_hi, 0x33333333
	s_nop 0
	v_cndmask_b32_dpp v50, v172, v176, vcc quad_perm:[2,3,0,1] row_mask:0xf bank_mask:0xf
	v_cndmask_b32_dpp v51, v170, v174, vcc quad_perm:[2,3,0,1] row_mask:0xf bank_mask:0xf
	s_mov_b32 vcc_lo, 0xcccccccc
	s_mov_b32 vcc_hi, 0xcccccccc
	v_cndmask_b32_dpp v52, v176, v172, vcc quad_perm:[2,3,0,1] row_mask:0xf bank_mask:0xf
	v_cndmask_b32_dpp v53, v174, v170, vcc quad_perm:[2,3,0,1] row_mask:0xf bank_mask:0xf
	s_mov_b32 vcc_lo, 0x55555555
	s_mov_b32 vcc_hi, 0x55555555
	v_cndmask_b32_dpp v176, v55, v54, vcc quad_perm:[1,0,3,2] row_mask:0xf bank_mask:0xf
	v_cndmask_b32_dpp v172, v57, v56, vcc quad_perm:[1,0,3,2] row_mask:0xf bank_mask:0xf
	s_mov_b32 vcc_lo, 0xaaaaaaaa
	s_mov_b32 vcc_hi, 0xaaaaaaaa
	v_cndmask_b32_dpp v174, v54, v55, vcc quad_perm:[1,0,3,2] row_mask:0xf bank_mask:0xf
	v_cndmask_b32_dpp v170, v56, v57, vcc quad_perm:[1,0,3,2] row_mask:0xf bank_mask:0xf
	s_mov_b32 vcc_lo, 0x33333333
	s_mov_b32 vcc_hi, 0x33333333
	s_nop 0
	v_cndmask_b32_dpp v54, v172, v176, vcc quad_perm:[2,3,0,1] row_mask:0xf bank_mask:0xf
	v_cndmask_b32_dpp v55, v170, v174, vcc quad_perm:[2,3,0,1] row_mask:0xf bank_mask:0xf
	s_mov_b32 vcc_lo, 0xcccccccc
	s_mov_b32 vcc_hi, 0xcccccccc
	v_cndmask_b32_dpp v56, v176, v172, vcc quad_perm:[2,3,0,1] row_mask:0xf bank_mask:0xf
	v_cndmask_b32_dpp v57, v174, v170, vcc quad_perm:[2,3,0,1] row_mask:0xf bank_mask:0xf
	v_mul_lo_u32 v163, s71, v167
	v_mad_u64_u32 v[186:187], s[38:39], s70, v167, 0
	v_add3_u32 v187, v187, v123, v163
	v_lshl_add_u64 v[186:187], v[186:187], 2, v[156:157]
	v_and_b32_e32 v186, 0xfffffff0, v186
	global_store_dwordx4 v[186:187], v[50:53], off
	v_or_b32_e32 v167, 4, v167
	v_mul_lo_u32 v163, s71, v167
	v_mad_u64_u32 v[186:187], s[38:39], s70, v167, 0
	v_add3_u32 v187, v187, v123, v163
	v_lshl_add_u64 v[186:187], v[186:187], 2, v[156:157]
	v_and_b32_e32 v186, 0xfffffff0, v186
	global_store_dwordx4 v[186:187], v[54:57], off
.LBB0_730:
	v_lshl_add_u64 v[158:159], v[158:159], 0, v[126:127]
	v_mov_b32_e32 v129, v1
	v_cvt_pk_bf16_f32 v186, v42, v43
	v_cvt_pk_bf16_f32 v187, v44, v45
	v_cvt_pk_bf16_f32 v188, v46, v47
	v_cvt_pk_bf16_f32 v189, v48, v49
	v_lshl_add_u64 v[158:159], v[158:159], 0, v[128:129]
	s_and_b64 vcc, exec, s[0:1]
	global_store_dwordx4 v[158:159], v[186:189], off
	s_cbranch_vccnz .LBB0_732
	v_mul_lo_u32 v123, s70, v185
	v_and_b32_e32 v173, 3, v168
	v_or_b32_e32 v173, v183, v173
	s_mov_b32 vcc_lo, 0x55555555
	s_mov_b32 vcc_hi, 0x55555555
	v_cndmask_b32_dpp v182, v43, v42, vcc quad_perm:[1,0,3,2] row_mask:0xf bank_mask:0xf
	v_cndmask_b32_dpp v179, v45, v44, vcc quad_perm:[1,0,3,2] row_mask:0xf bank_mask:0xf
	s_mov_b32 vcc_lo, 0xaaaaaaaa
	s_mov_b32 vcc_hi, 0xaaaaaaaa
	v_cndmask_b32_dpp v181, v42, v43, vcc quad_perm:[1,0,3,2] row_mask:0xf bank_mask:0xf
	v_cndmask_b32_dpp v175, v44, v45, vcc quad_perm:[1,0,3,2] row_mask:0xf bank_mask:0xf
	s_mov_b32 vcc_lo, 0x33333333
	s_mov_b32 vcc_hi, 0x33333333
	s_nop 0
	v_cndmask_b32_dpp v42, v179, v182, vcc quad_perm:[2,3,0,1] row_mask:0xf bank_mask:0xf
	v_cndmask_b32_dpp v43, v175, v181, vcc quad_perm:[2,3,0,1] row_mask:0xf bank_mask:0xf
	s_mov_b32 vcc_lo, 0xcccccccc
	s_mov_b32 vcc_hi, 0xcccccccc
	v_cndmask_b32_dpp v44, v182, v179, vcc quad_perm:[2,3,0,1] row_mask:0xf bank_mask:0xf
	v_cndmask_b32_dpp v45, v181, v175, vcc quad_perm:[2,3,0,1] row_mask:0xf bank_mask:0xf
	s_mov_b32 vcc_lo, 0x55555555
	s_mov_b32 vcc_hi, 0x55555555
	v_cndmask_b32_dpp v182, v47, v46, vcc quad_perm:[1,0,3,2] row_mask:0xf bank_mask:0xf
	v_cndmask_b32_dpp v179, v49, v48, vcc quad_perm:[1,0,3,2] row_mask:0xf bank_mask:0xf
	s_mov_b32 vcc_lo, 0xaaaaaaaa
	s_mov_b32 vcc_hi, 0xaaaaaaaa
	v_cndmask_b32_dpp v181, v46, v47, vcc quad_perm:[1,0,3,2] row_mask:0xf bank_mask:0xf
	v_cndmask_b32_dpp v175, v48, v49, vcc quad_perm:[1,0,3,2] row_mask:0xf bank_mask:0xf
	s_mov_b32 vcc_lo, 0x33333333
	s_mov_b32 vcc_hi, 0x33333333
	s_nop 0
	v_cndmask_b32_dpp v46, v179, v182, vcc quad_perm:[2,3,0,1] row_mask:0xf bank_mask:0xf
	v_cndmask_b32_dpp v47, v175, v181, vcc quad_perm:[2,3,0,1] row_mask:0xf bank_mask:0xf
	s_mov_b32 vcc_lo, 0xcccccccc
	s_mov_b32 vcc_hi, 0xcccccccc
	v_cndmask_b32_dpp v48, v182, v179, vcc quad_perm:[2,3,0,1] row_mask:0xf bank_mask:0xf
	v_cndmask_b32_dpp v49, v181, v175, vcc quad_perm:[2,3,0,1] row_mask:0xf bank_mask:0xf
	v_mul_lo_u32 v171, s71, v173
	v_mad_u64_u32 v[158:159], s[38:39], s70, v173, 0
	v_add3_u32 v159, v159, v123, v171
	v_lshl_add_u64 v[158:159], v[158:159], 2, v[156:157]
	v_and_b32_e32 v158, 0xfffffff0, v158
	global_store_dwordx4 v[158:159], v[42:45], off
	v_or_b32_e32 v173, 4, v173
	v_mul_lo_u32 v171, s71, v173
	v_mad_u64_u32 v[158:159], s[38:39], s70, v173, 0
	v_add3_u32 v159, v159, v123, v171
	v_lshl_add_u64 v[158:159], v[158:159], 2, v[156:157]
	v_and_b32_e32 v158, 0xfffffff0, v158
	global_store_dwordx4 v[158:159], v[46:49], off
.LBB0_732:
	v_add_u32_e32 v156, 0x90, v122
	v_ashrrev_i32_e32 v123, s81, v156
	v_add_u32_e32 v123, s6, v123
	v_mul_lo_u32 v158, v123, s10
	v_ashrrev_i32_e32 v159, 31, v158
	v_lshlrev_b64 v[158:159], s81, v[158:159]
	v_and_or_b32 v158, v156, s2, v158
	v_lshlrev_b64 v[158:159], 6, v[158:159]
	v_lshl_add_u64 v[158:159], s[36:37], 0, v[158:159]
	v_ashrrev_i32_e32 v157, 31, v156
	v_lshl_add_u64 v[190:191], v[158:159], 0, v[124:125]
	v_cvt_pk_bf16_f32 v186, v34, v35
	v_cvt_pk_bf16_f32 v187, v36, v37
	v_cvt_pk_bf16_f32 v188, v38, v39
	v_cvt_pk_bf16_f32 v189, v40, v41
	v_lshl_add_u64 v[190:191], v[190:191], 0, v[0:1]
	s_and_b64 vcc, exec, s[0:1]
	v_lshl_add_u64 v[156:157], v[156:157], 2, s[66:67]
	global_store_dwordx4 v[190:191], v[186:189], off
	s_cbranch_vccnz .LBB0_734
	v_mul_lo_u32 v123, s70, v180
	v_and_b32_e32 v167, 3, v168
	v_or_b32_e32 v167, v177, v167
	s_mov_b32 vcc_lo, 0x55555555
	s_mov_b32 vcc_hi, 0x55555555
	v_cndmask_b32_dpp v176, v35, v34, vcc quad_perm:[1,0,3,2] row_mask:0xf bank_mask:0xf
	v_cndmask_b32_dpp v172, v37, v36, vcc quad_perm:[1,0,3,2] row_mask:0xf bank_mask:0xf
	s_mov_b32 vcc_lo, 0xaaaaaaaa
	s_mov_b32 vcc_hi, 0xaaaaaaaa
	v_cndmask_b32_dpp v174, v34, v35, vcc quad_perm:[1,0,3,2] row_mask:0xf bank_mask:0xf
	v_cndmask_b32_dpp v170, v36, v37, vcc quad_perm:[1,0,3,2] row_mask:0xf bank_mask:0xf
	s_mov_b32 vcc_lo, 0x33333333
	s_mov_b32 vcc_hi, 0x33333333
	s_nop 0
	v_cndmask_b32_dpp v34, v172, v176, vcc quad_perm:[2,3,0,1] row_mask:0xf bank_mask:0xf
	v_cndmask_b32_dpp v35, v170, v174, vcc quad_perm:[2,3,0,1] row_mask:0xf bank_mask:0xf
	s_mov_b32 vcc_lo, 0xcccccccc
	s_mov_b32 vcc_hi, 0xcccccccc
	v_cndmask_b32_dpp v36, v176, v172, vcc quad_perm:[2,3,0,1] row_mask:0xf bank_mask:0xf
	v_cndmask_b32_dpp v37, v174, v170, vcc quad_perm:[2,3,0,1] row_mask:0xf bank_mask:0xf
	s_mov_b32 vcc_lo, 0x55555555
	s_mov_b32 vcc_hi, 0x55555555
	v_cndmask_b32_dpp v176, v39, v38, vcc quad_perm:[1,0,3,2] row_mask:0xf bank_mask:0xf
	v_cndmask_b32_dpp v172, v41, v40, vcc quad_perm:[1,0,3,2] row_mask:0xf bank_mask:0xf
	s_mov_b32 vcc_lo, 0xaaaaaaaa
	s_mov_b32 vcc_hi, 0xaaaaaaaa
	v_cndmask_b32_dpp v174, v38, v39, vcc quad_perm:[1,0,3,2] row_mask:0xf bank_mask:0xf
	v_cndmask_b32_dpp v170, v40, v41, vcc quad_perm:[1,0,3,2] row_mask:0xf bank_mask:0xf
	s_mov_b32 vcc_lo, 0x33333333
	s_mov_b32 vcc_hi, 0x33333333
	s_nop 0
	v_cndmask_b32_dpp v38, v172, v176, vcc quad_perm:[2,3,0,1] row_mask:0xf bank_mask:0xf
	v_cndmask_b32_dpp v39, v170, v174, vcc quad_perm:[2,3,0,1] row_mask:0xf bank_mask:0xf
	s_mov_b32 vcc_lo, 0xcccccccc
	s_mov_b32 vcc_hi, 0xcccccccc
	v_cndmask_b32_dpp v40, v176, v172, vcc quad_perm:[2,3,0,1] row_mask:0xf bank_mask:0xf
	v_cndmask_b32_dpp v41, v174, v170, vcc quad_perm:[2,3,0,1] row_mask:0xf bank_mask:0xf
	v_mul_lo_u32 v163, s71, v167
	v_mad_u64_u32 v[186:187], s[38:39], s70, v167, 0
	v_add3_u32 v187, v187, v123, v163
	v_lshl_add_u64 v[186:187], v[186:187], 2, v[156:157]
	v_and_b32_e32 v186, 0xfffffff0, v186
	global_store_dwordx4 v[186:187], v[34:37], off
	v_or_b32_e32 v167, 4, v167
	v_mul_lo_u32 v163, s71, v167
	v_mad_u64_u32 v[186:187], s[38:39], s70, v167, 0
	v_add3_u32 v187, v187, v123, v163
	v_lshl_add_u64 v[186:187], v[186:187], 2, v[156:157]
	v_and_b32_e32 v186, 0xfffffff0, v186
	global_store_dwordx4 v[186:187], v[38:41], off
.LBB0_734:
	v_lshl_add_u64 v[158:159], v[158:159], 0, v[126:127]
	v_mov_b32_e32 v129, v1
	v_cvt_pk_bf16_f32 v186, v26, v27
	v_cvt_pk_bf16_f32 v187, v28, v29
	v_cvt_pk_bf16_f32 v188, v30, v31
	v_cvt_pk_bf16_f32 v189, v32, v33
	v_lshl_add_u64 v[158:159], v[158:159], 0, v[128:129]
	s_and_b64 vcc, exec, s[0:1]
	global_store_dwordx4 v[158:159], v[186:189], off
	s_cbranch_vccnz .LBB0_736
	v_mul_lo_u32 v123, s70, v185
	v_and_b32_e32 v173, 3, v168
	v_or_b32_e32 v173, v183, v173
	s_mov_b32 vcc_lo, 0x55555555
	s_mov_b32 vcc_hi, 0x55555555
	v_cndmask_b32_dpp v182, v27, v26, vcc quad_perm:[1,0,3,2] row_mask:0xf bank_mask:0xf
	v_cndmask_b32_dpp v179, v29, v28, vcc quad_perm:[1,0,3,2] row_mask:0xf bank_mask:0xf
	s_mov_b32 vcc_lo, 0xaaaaaaaa
	s_mov_b32 vcc_hi, 0xaaaaaaaa
	v_cndmask_b32_dpp v181, v26, v27, vcc quad_perm:[1,0,3,2] row_mask:0xf bank_mask:0xf
	v_cndmask_b32_dpp v175, v28, v29, vcc quad_perm:[1,0,3,2] row_mask:0xf bank_mask:0xf
	s_mov_b32 vcc_lo, 0x33333333
	s_mov_b32 vcc_hi, 0x33333333
	s_nop 0
	v_cndmask_b32_dpp v26, v179, v182, vcc quad_perm:[2,3,0,1] row_mask:0xf bank_mask:0xf
	v_cndmask_b32_dpp v27, v175, v181, vcc quad_perm:[2,3,0,1] row_mask:0xf bank_mask:0xf
	s_mov_b32 vcc_lo, 0xcccccccc
	s_mov_b32 vcc_hi, 0xcccccccc
	v_cndmask_b32_dpp v28, v182, v179, vcc quad_perm:[2,3,0,1] row_mask:0xf bank_mask:0xf
	v_cndmask_b32_dpp v29, v181, v175, vcc quad_perm:[2,3,0,1] row_mask:0xf bank_mask:0xf
	s_mov_b32 vcc_lo, 0x55555555
	s_mov_b32 vcc_hi, 0x55555555
	v_cndmask_b32_dpp v182, v31, v30, vcc quad_perm:[1,0,3,2] row_mask:0xf bank_mask:0xf
	v_cndmask_b32_dpp v179, v33, v32, vcc quad_perm:[1,0,3,2] row_mask:0xf bank_mask:0xf
	s_mov_b32 vcc_lo, 0xaaaaaaaa
	s_mov_b32 vcc_hi, 0xaaaaaaaa
	v_cndmask_b32_dpp v181, v30, v31, vcc quad_perm:[1,0,3,2] row_mask:0xf bank_mask:0xf
	v_cndmask_b32_dpp v175, v32, v33, vcc quad_perm:[1,0,3,2] row_mask:0xf bank_mask:0xf
	s_mov_b32 vcc_lo, 0x33333333
	s_mov_b32 vcc_hi, 0x33333333
	s_nop 0
	v_cndmask_b32_dpp v30, v179, v182, vcc quad_perm:[2,3,0,1] row_mask:0xf bank_mask:0xf
	v_cndmask_b32_dpp v31, v175, v181, vcc quad_perm:[2,3,0,1] row_mask:0xf bank_mask:0xf
	s_mov_b32 vcc_lo, 0xcccccccc
	s_mov_b32 vcc_hi, 0xcccccccc
	v_cndmask_b32_dpp v32, v182, v179, vcc quad_perm:[2,3,0,1] row_mask:0xf bank_mask:0xf
	v_cndmask_b32_dpp v33, v181, v175, vcc quad_perm:[2,3,0,1] row_mask:0xf bank_mask:0xf
	v_mul_lo_u32 v171, s71, v173
	v_mad_u64_u32 v[158:159], s[38:39], s70, v173, 0
	v_add3_u32 v159, v159, v123, v171
	v_lshl_add_u64 v[158:159], v[158:159], 2, v[156:157]
	v_and_b32_e32 v158, 0xfffffff0, v158
	global_store_dwordx4 v[158:159], v[26:29], off
	v_or_b32_e32 v173, 4, v173
	v_mul_lo_u32 v171, s71, v173
	v_mad_u64_u32 v[158:159], s[38:39], s70, v173, 0
	v_add3_u32 v159, v159, v123, v171
	v_lshl_add_u64 v[158:159], v[158:159], 2, v[156:157]
	v_and_b32_e32 v158, 0xfffffff0, v158
	global_store_dwordx4 v[158:159], v[30:33], off
.LBB0_736:
	v_add_u32_e32 v156, 0xa0, v122
	v_ashrrev_i32_e32 v123, s81, v156
	v_add_u32_e32 v123, s6, v123
	v_mul_lo_u32 v158, v123, s10
	v_ashrrev_i32_e32 v159, 31, v158
	v_lshlrev_b64 v[158:159], s81, v[158:159]
	v_and_or_b32 v158, v156, s2, v158
	v_lshlrev_b64 v[158:159], 6, v[158:159]
	v_lshl_add_u64 v[158:159], s[36:37], 0, v[158:159]
	v_ashrrev_i32_e32 v157, 31, v156
	v_lshl_add_u64 v[190:191], v[158:159], 0, v[124:125]
	v_cvt_pk_bf16_f32 v186, v18, v19
	v_cvt_pk_bf16_f32 v187, v20, v21
	v_cvt_pk_bf16_f32 v188, v22, v23
	v_cvt_pk_bf16_f32 v189, v24, v25
	v_lshl_add_u64 v[190:191], v[190:191], 0, v[0:1]
	s_and_b64 vcc, exec, s[0:1]
	v_lshl_add_u64 v[156:157], v[156:157], 2, s[66:67]
	global_store_dwordx4 v[190:191], v[186:189], off
	s_cbranch_vccnz .LBB0_738
	v_mul_lo_u32 v123, s70, v180
	v_and_b32_e32 v167, 3, v168
	v_or_b32_e32 v167, v177, v167
	s_mov_b32 vcc_lo, 0x55555555
	s_mov_b32 vcc_hi, 0x55555555
	v_cndmask_b32_dpp v176, v19, v18, vcc quad_perm:[1,0,3,2] row_mask:0xf bank_mask:0xf
	v_cndmask_b32_dpp v172, v21, v20, vcc quad_perm:[1,0,3,2] row_mask:0xf bank_mask:0xf
	s_mov_b32 vcc_lo, 0xaaaaaaaa
	s_mov_b32 vcc_hi, 0xaaaaaaaa
	v_cndmask_b32_dpp v174, v18, v19, vcc quad_perm:[1,0,3,2] row_mask:0xf bank_mask:0xf
	v_cndmask_b32_dpp v170, v20, v21, vcc quad_perm:[1,0,3,2] row_mask:0xf bank_mask:0xf
	s_mov_b32 vcc_lo, 0x33333333
	s_mov_b32 vcc_hi, 0x33333333
	s_nop 0
	v_cndmask_b32_dpp v18, v172, v176, vcc quad_perm:[2,3,0,1] row_mask:0xf bank_mask:0xf
	v_cndmask_b32_dpp v19, v170, v174, vcc quad_perm:[2,3,0,1] row_mask:0xf bank_mask:0xf
	s_mov_b32 vcc_lo, 0xcccccccc
	s_mov_b32 vcc_hi, 0xcccccccc
	v_cndmask_b32_dpp v20, v176, v172, vcc quad_perm:[2,3,0,1] row_mask:0xf bank_mask:0xf
	v_cndmask_b32_dpp v21, v174, v170, vcc quad_perm:[2,3,0,1] row_mask:0xf bank_mask:0xf
	s_mov_b32 vcc_lo, 0x55555555
	s_mov_b32 vcc_hi, 0x55555555
	v_cndmask_b32_dpp v176, v23, v22, vcc quad_perm:[1,0,3,2] row_mask:0xf bank_mask:0xf
	v_cndmask_b32_dpp v172, v25, v24, vcc quad_perm:[1,0,3,2] row_mask:0xf bank_mask:0xf
	s_mov_b32 vcc_lo, 0xaaaaaaaa
	s_mov_b32 vcc_hi, 0xaaaaaaaa
	v_cndmask_b32_dpp v174, v22, v23, vcc quad_perm:[1,0,3,2] row_mask:0xf bank_mask:0xf
	v_cndmask_b32_dpp v170, v24, v25, vcc quad_perm:[1,0,3,2] row_mask:0xf bank_mask:0xf
	s_mov_b32 vcc_lo, 0x33333333
	s_mov_b32 vcc_hi, 0x33333333
	s_nop 0
	v_cndmask_b32_dpp v22, v172, v176, vcc quad_perm:[2,3,0,1] row_mask:0xf bank_mask:0xf
	v_cndmask_b32_dpp v23, v170, v174, vcc quad_perm:[2,3,0,1] row_mask:0xf bank_mask:0xf
	s_mov_b32 vcc_lo, 0xcccccccc
	s_mov_b32 vcc_hi, 0xcccccccc
	v_cndmask_b32_dpp v24, v176, v172, vcc quad_perm:[2,3,0,1] row_mask:0xf bank_mask:0xf
	v_cndmask_b32_dpp v25, v174, v170, vcc quad_perm:[2,3,0,1] row_mask:0xf bank_mask:0xf
	v_mul_lo_u32 v163, s71, v167
	v_mad_u64_u32 v[186:187], s[38:39], s70, v167, 0
	v_add3_u32 v187, v187, v123, v163
	v_lshl_add_u64 v[186:187], v[186:187], 2, v[156:157]
	v_and_b32_e32 v186, 0xfffffff0, v186
	global_store_dwordx4 v[186:187], v[18:21], off
	v_or_b32_e32 v167, 4, v167
	v_mul_lo_u32 v163, s71, v167
	v_mad_u64_u32 v[186:187], s[38:39], s70, v167, 0
	v_add3_u32 v187, v187, v123, v163
	v_lshl_add_u64 v[186:187], v[186:187], 2, v[156:157]
	v_and_b32_e32 v186, 0xfffffff0, v186
	global_store_dwordx4 v[186:187], v[22:25], off
.LBB0_738:
	v_lshl_add_u64 v[158:159], v[158:159], 0, v[126:127]
	v_mov_b32_e32 v129, v1
	v_cvt_pk_bf16_f32 v186, v10, v11
	v_cvt_pk_bf16_f32 v187, v12, v13
	v_cvt_pk_bf16_f32 v188, v14, v15
	v_cvt_pk_bf16_f32 v189, v16, v17
	v_lshl_add_u64 v[158:159], v[158:159], 0, v[128:129]
	s_and_b64 vcc, exec, s[0:1]
	global_store_dwordx4 v[158:159], v[186:189], off
	s_cbranch_vccnz .LBB0_740
	v_mul_lo_u32 v123, s70, v185
	v_and_b32_e32 v173, 3, v168
	v_or_b32_e32 v173, v183, v173
	s_mov_b32 vcc_lo, 0x55555555
	s_mov_b32 vcc_hi, 0x55555555
	v_cndmask_b32_dpp v182, v11, v10, vcc quad_perm:[1,0,3,2] row_mask:0xf bank_mask:0xf
	v_cndmask_b32_dpp v179, v13, v12, vcc quad_perm:[1,0,3,2] row_mask:0xf bank_mask:0xf
	s_mov_b32 vcc_lo, 0xaaaaaaaa
	s_mov_b32 vcc_hi, 0xaaaaaaaa
	v_cndmask_b32_dpp v181, v10, v11, vcc quad_perm:[1,0,3,2] row_mask:0xf bank_mask:0xf
	v_cndmask_b32_dpp v175, v12, v13, vcc quad_perm:[1,0,3,2] row_mask:0xf bank_mask:0xf
	s_mov_b32 vcc_lo, 0x33333333
	s_mov_b32 vcc_hi, 0x33333333
	s_nop 0
	v_cndmask_b32_dpp v10, v179, v182, vcc quad_perm:[2,3,0,1] row_mask:0xf bank_mask:0xf
	v_cndmask_b32_dpp v11, v175, v181, vcc quad_perm:[2,3,0,1] row_mask:0xf bank_mask:0xf
	s_mov_b32 vcc_lo, 0xcccccccc
	s_mov_b32 vcc_hi, 0xcccccccc
	v_cndmask_b32_dpp v12, v182, v179, vcc quad_perm:[2,3,0,1] row_mask:0xf bank_mask:0xf
	v_cndmask_b32_dpp v13, v181, v175, vcc quad_perm:[2,3,0,1] row_mask:0xf bank_mask:0xf
	s_mov_b32 vcc_lo, 0x55555555
	s_mov_b32 vcc_hi, 0x55555555
	v_cndmask_b32_dpp v182, v15, v14, vcc quad_perm:[1,0,3,2] row_mask:0xf bank_mask:0xf
	v_cndmask_b32_dpp v179, v17, v16, vcc quad_perm:[1,0,3,2] row_mask:0xf bank_mask:0xf
	s_mov_b32 vcc_lo, 0xaaaaaaaa
	s_mov_b32 vcc_hi, 0xaaaaaaaa
	v_cndmask_b32_dpp v181, v14, v15, vcc quad_perm:[1,0,3,2] row_mask:0xf bank_mask:0xf
	v_cndmask_b32_dpp v175, v16, v17, vcc quad_perm:[1,0,3,2] row_mask:0xf bank_mask:0xf
	s_mov_b32 vcc_lo, 0x33333333
	s_mov_b32 vcc_hi, 0x33333333
	s_nop 0
	v_cndmask_b32_dpp v14, v179, v182, vcc quad_perm:[2,3,0,1] row_mask:0xf bank_mask:0xf
	v_cndmask_b32_dpp v15, v175, v181, vcc quad_perm:[2,3,0,1] row_mask:0xf bank_mask:0xf
	s_mov_b32 vcc_lo, 0xcccccccc
	s_mov_b32 vcc_hi, 0xcccccccc
	v_cndmask_b32_dpp v16, v182, v179, vcc quad_perm:[2,3,0,1] row_mask:0xf bank_mask:0xf
	v_cndmask_b32_dpp v17, v181, v175, vcc quad_perm:[2,3,0,1] row_mask:0xf bank_mask:0xf
	v_mul_lo_u32 v171, s71, v173
	v_mad_u64_u32 v[158:159], s[38:39], s70, v173, 0
	v_add3_u32 v159, v159, v123, v171
	v_lshl_add_u64 v[158:159], v[158:159], 2, v[156:157]
	v_and_b32_e32 v158, 0xfffffff0, v158
	global_store_dwordx4 v[158:159], v[10:13], off
	v_or_b32_e32 v173, 4, v173
	v_mul_lo_u32 v171, s71, v173
	v_mad_u64_u32 v[158:159], s[38:39], s70, v173, 0
	v_add3_u32 v159, v159, v123, v171
	v_lshl_add_u64 v[158:159], v[158:159], 2, v[156:157]
	v_and_b32_e32 v158, 0xfffffff0, v158
	global_store_dwordx4 v[158:159], v[14:17], off
.LBB0_740:
	v_add_u32_e32 v122, 0xb0, v122
	v_ashrrev_i32_e32 v123, s81, v122
	v_add_u32_e32 v123, s6, v123
	v_mul_lo_u32 v156, v123, s10
	v_ashrrev_i32_e32 v157, 31, v156
	v_lshlrev_b64 v[156:157], s81, v[156:157]
	v_and_or_b32 v156, v122, s2, v156
	v_lshlrev_b64 v[156:157], 6, v[156:157]
	v_lshl_add_u64 v[156:157], s[36:37], 0, v[156:157]
	v_ashrrev_i32_e32 v123, 31, v122
	v_lshl_add_u64 v[124:125], v[156:157], 0, v[124:125]
	v_cvt_pk_bf16_f32 v186, v2, v3
	v_cvt_pk_bf16_f32 v187, v4, v5
	v_cvt_pk_bf16_f32 v188, v6, v7
	v_cvt_pk_bf16_f32 v189, v8, v9
	v_lshl_add_u64 v[124:125], v[124:125], 0, v[0:1]
	s_and_b64 vcc, exec, s[0:1]
	v_lshl_add_u64 v[122:123], v[122:123], 2, s[66:67]
	global_store_dwordx4 v[124:125], v[186:189], off
	s_cbranch_vccnz .LBB0_742
	v_mul_lo_u32 v0, s70, v180
	v_and_b32_e32 v167, 3, v168
	v_or_b32_e32 v167, v177, v167
	s_mov_b32 vcc_lo, 0x55555555
	s_mov_b32 vcc_hi, 0x55555555
	v_cndmask_b32_dpp v176, v3, v2, vcc quad_perm:[1,0,3,2] row_mask:0xf bank_mask:0xf
	v_cndmask_b32_dpp v172, v5, v4, vcc quad_perm:[1,0,3,2] row_mask:0xf bank_mask:0xf
	s_mov_b32 vcc_lo, 0xaaaaaaaa
	s_mov_b32 vcc_hi, 0xaaaaaaaa
	v_cndmask_b32_dpp v174, v2, v3, vcc quad_perm:[1,0,3,2] row_mask:0xf bank_mask:0xf
	v_cndmask_b32_dpp v170, v4, v5, vcc quad_perm:[1,0,3,2] row_mask:0xf bank_mask:0xf
	s_mov_b32 vcc_lo, 0x33333333
	s_mov_b32 vcc_hi, 0x33333333
	s_nop 0
	v_cndmask_b32_dpp v2, v172, v176, vcc quad_perm:[2,3,0,1] row_mask:0xf bank_mask:0xf
	v_cndmask_b32_dpp v3, v170, v174, vcc quad_perm:[2,3,0,1] row_mask:0xf bank_mask:0xf
	s_mov_b32 vcc_lo, 0xcccccccc
	s_mov_b32 vcc_hi, 0xcccccccc
	v_cndmask_b32_dpp v4, v176, v172, vcc quad_perm:[2,3,0,1] row_mask:0xf bank_mask:0xf
	v_cndmask_b32_dpp v5, v174, v170, vcc quad_perm:[2,3,0,1] row_mask:0xf bank_mask:0xf
	s_mov_b32 vcc_lo, 0x55555555
	s_mov_b32 vcc_hi, 0x55555555
	v_cndmask_b32_dpp v176, v7, v6, vcc quad_perm:[1,0,3,2] row_mask:0xf bank_mask:0xf
	v_cndmask_b32_dpp v172, v9, v8, vcc quad_perm:[1,0,3,2] row_mask:0xf bank_mask:0xf
	s_mov_b32 vcc_lo, 0xaaaaaaaa
	s_mov_b32 vcc_hi, 0xaaaaaaaa
	v_cndmask_b32_dpp v174, v6, v7, vcc quad_perm:[1,0,3,2] row_mask:0xf bank_mask:0xf
	v_cndmask_b32_dpp v170, v8, v9, vcc quad_perm:[1,0,3,2] row_mask:0xf bank_mask:0xf
	s_mov_b32 vcc_lo, 0x33333333
	s_mov_b32 vcc_hi, 0x33333333
	s_nop 0
	v_cndmask_b32_dpp v6, v172, v176, vcc quad_perm:[2,3,0,1] row_mask:0xf bank_mask:0xf
	v_cndmask_b32_dpp v7, v170, v174, vcc quad_perm:[2,3,0,1] row_mask:0xf bank_mask:0xf
	s_mov_b32 vcc_lo, 0xcccccccc
	s_mov_b32 vcc_hi, 0xcccccccc
	v_cndmask_b32_dpp v8, v176, v172, vcc quad_perm:[2,3,0,1] row_mask:0xf bank_mask:0xf
	v_cndmask_b32_dpp v9, v174, v170, vcc quad_perm:[2,3,0,1] row_mask:0xf bank_mask:0xf
	v_mul_lo_u32 v163, s71, v167
	v_mad_u64_u32 v[124:125], s[6:7], s70, v167, 0
	v_add3_u32 v125, v125, v0, v163
	v_lshl_add_u64 v[124:125], v[124:125], 2, v[122:123]
	v_and_b32_e32 v124, 0xfffffff0, v124
	global_store_dwordx4 v[124:125], v[2:5], off
	v_or_b32_e32 v167, 4, v167
	v_mul_lo_u32 v163, s71, v167
	v_mad_u64_u32 v[124:125], s[6:7], s70, v167, 0
	v_add3_u32 v125, v125, v0, v163
	v_lshl_add_u64 v[124:125], v[124:125], 2, v[122:123]
	v_and_b32_e32 v124, 0xfffffff0, v124
	global_store_dwordx4 v[124:125], v[6:9], off
.LBB0_742:
	v_lshl_add_u64 v[124:125], v[156:157], 0, v[126:127]
	v_mov_b32_e32 v129, v1
	v_cvt_pk_bf16_f32 v186, v134, v135
	v_cvt_pk_bf16_f32 v187, v136, v137
	v_cvt_pk_bf16_f32 v188, v130, v131
	v_cvt_pk_bf16_f32 v189, v132, v133
	v_lshl_add_u64 v[124:125], v[124:125], 0, v[128:129]
	s_and_b64 vcc, exec, s[0:1]
	global_store_dwordx4 v[124:125], v[186:189], off
	s_cbranch_vccnz .LBB0_744
	v_mul_lo_u32 v0, s70, v185
	v_and_b32_e32 v173, 3, v168
	v_or_b32_e32 v173, v183, v173
	s_mov_b32 vcc_lo, 0x55555555
	s_mov_b32 vcc_hi, 0x55555555
	v_cndmask_b32_dpp v182, v135, v134, vcc quad_perm:[1,0,3,2] row_mask:0xf bank_mask:0xf
	v_cndmask_b32_dpp v179, v137, v136, vcc quad_perm:[1,0,3,2] row_mask:0xf bank_mask:0xf
	s_mov_b32 vcc_lo, 0xaaaaaaaa
	s_mov_b32 vcc_hi, 0xaaaaaaaa
	v_cndmask_b32_dpp v181, v134, v135, vcc quad_perm:[1,0,3,2] row_mask:0xf bank_mask:0xf
	v_cndmask_b32_dpp v175, v136, v137, vcc quad_perm:[1,0,3,2] row_mask:0xf bank_mask:0xf
	s_mov_b32 vcc_lo, 0x33333333
	s_mov_b32 vcc_hi, 0x33333333
	s_nop 0
	v_cndmask_b32_dpp v134, v179, v182, vcc quad_perm:[2,3,0,1] row_mask:0xf bank_mask:0xf
	v_cndmask_b32_dpp v135, v175, v181, vcc quad_perm:[2,3,0,1] row_mask:0xf bank_mask:0xf
	s_mov_b32 vcc_lo, 0xcccccccc
	s_mov_b32 vcc_hi, 0xcccccccc
	v_cndmask_b32_dpp v136, v182, v179, vcc quad_perm:[2,3,0,1] row_mask:0xf bank_mask:0xf
	v_cndmask_b32_dpp v137, v181, v175, vcc quad_perm:[2,3,0,1] row_mask:0xf bank_mask:0xf
	s_mov_b32 vcc_lo, 0x55555555
	s_mov_b32 vcc_hi, 0x55555555
	v_cndmask_b32_dpp v182, v131, v130, vcc quad_perm:[1,0,3,2] row_mask:0xf bank_mask:0xf
	v_cndmask_b32_dpp v179, v133, v132, vcc quad_perm:[1,0,3,2] row_mask:0xf bank_mask:0xf
	s_mov_b32 vcc_lo, 0xaaaaaaaa
	s_mov_b32 vcc_hi, 0xaaaaaaaa
	v_cndmask_b32_dpp v181, v130, v131, vcc quad_perm:[1,0,3,2] row_mask:0xf bank_mask:0xf
	v_cndmask_b32_dpp v175, v132, v133, vcc quad_perm:[1,0,3,2] row_mask:0xf bank_mask:0xf
	s_mov_b32 vcc_lo, 0x33333333
	s_mov_b32 vcc_hi, 0x33333333
	s_nop 0
	v_cndmask_b32_dpp v130, v179, v182, vcc quad_perm:[2,3,0,1] row_mask:0xf bank_mask:0xf
	v_cndmask_b32_dpp v131, v175, v181, vcc quad_perm:[2,3,0,1] row_mask:0xf bank_mask:0xf
	s_mov_b32 vcc_lo, 0xcccccccc
	s_mov_b32 vcc_hi, 0xcccccccc
	v_cndmask_b32_dpp v132, v182, v179, vcc quad_perm:[2,3,0,1] row_mask:0xf bank_mask:0xf
	v_cndmask_b32_dpp v133, v181, v175, vcc quad_perm:[2,3,0,1] row_mask:0xf bank_mask:0xf
	v_mul_lo_u32 v171, s71, v173
	v_mad_u64_u32 v[124:125], s[0:1], s70, v173, 0
	v_add3_u32 v125, v125, v0, v171
	v_lshl_add_u64 v[124:125], v[124:125], 2, v[122:123]
	v_and_b32_e32 v124, 0xfffffff0, v124
	global_store_dwordx4 v[124:125], v[134:137], off
	v_or_b32_e32 v173, 4, v173
	v_mul_lo_u32 v171, s71, v173
	v_mad_u64_u32 v[124:125], s[0:1], s70, v173, 0
	v_add3_u32 v125, v125, v0, v171
	v_lshl_add_u64 v[124:125], v[124:125], 2, v[122:123]
	v_and_b32_e32 v124, 0xfffffff0, v124
	global_store_dwordx4 v[124:125], v[130:133], off
